# diff producer: tile staging (LDS writes + next global loads) interleaved into its P.V MFMA block; on top of v101
# baseline (speedup 1.0000x reference)
; #define SBAR() __builtin_amdgcn_sched_barrier(0)
; template <int D0> __device__ __forceinline__ void pv_one(f32x16& od, int vb, bf16x8 pa0, bf16x8 pa1, bf16x8 pa2, bf16x8 pa3) {
;   const s16x4 l0 = tr_read<v_rd_off(D0, 0, 0)>(vb), h0 = tr_read<v_rd_off(D0, 0, 1)>(vb), l1 = tr_read<v_rd_off(D0, 1, 0)>(vb), h1 = tr_read<v_rd_off(D0, 1, 1)>(vb);
;   const s16x4 l2 = tr_read<v_rd_off(D0, 2, 0)>(vb), h2 = tr_read<v_rd_off(D0, 2, 1)>(vb), l3 = tr_read<v_rd_off(D0, 3, 0)>(vb), h3 = tr_read<v_rd_off(D0, 3, 1)>(vb);
;   asm volatile("s_waitcnt lgkmcnt(0)" ::: "memory"); SBAR();
;     ...
;   od = __builtin_amdgcn_mfma_f32_32x32x16_bf16(pa0, PK(l0, h0), od, 0, 0, 0);
;   od = __builtin_amdgcn_mfma_f32_32x32x16_bf16(pa1, PK(l1, h1), od, 0, 0, 0);
;   od = __builtin_amdgcn_mfma_f32_32x32x16_bf16(pa2, PK(l2, h2), od, 0, 0, 0);
;   od = __builtin_amdgcn_mfma_f32_32x32x16_bf16(pa3, PK(l3, h3), od, 0, 0, 0);
;     ...
; }
; __device__ __forceinline__ void pv_d0(f32x16* o, int vb, bf16x8 pa0, bf16x8 pa1, bf16x8 pa2, bf16x8 pa3) {
;   pv_one<0>(o[0], vb, pa0, pa1, pa2, pa3); pv_one<1>(o[1], vb, pa0, pa1, pa2, pa3); pv_one<2>(o[2], vb, pa0, pa1, pa2, pa3); pv_one<3>(o[3], vb, pa0, pa1, pa2, pa3);
.Ldiff_p_nors:
	s_cmp_eq_u32 s28, 0x3a0000
	s_cbranch_scc1 .Ldiff_p_plain
	s_or_b64 exec, exec, s[30:31]
	v_lshl_add_u32 v163, s16, 15, v204
	ds_read_b64_tr_b16 v[80:81], v163 offset:0
	ds_read_b64_tr_b16 v[82:83], v163 offset:0x800
	ds_read_b64_tr_b16 v[84:85], v163 offset:0x1000
	ds_read_b64_tr_b16 v[86:87], v163 offset:0x1800
	ds_read_b64_tr_b16 v[88:89], v163 offset:0x2000
	ds_read_b64_tr_b16 v[90:91], v163 offset:0x2800
	ds_read_b64_tr_b16 v[92:93], v163 offset:0x3000
	ds_read_b64_tr_b16 v[94:95], v163 offset:0x3800
	s_lshl_b32 s30, s57, 14
	s_xor_b32 s30, s30, 0x4000
	s_add_i32 s30, s30, 0
	v_add_u32_e32 v232, s30, v198
	s_waitcnt vmcnt(5)
	ds_write_b128 v232, v[128:131]
	s_waitcnt lgkmcnt(7)
	v_mfma_f32_32x32x16_bf16 v[48:63], v[240:243], v[80:83], v[48:63]
	v_add_u32_e32 v232, s30, v199
	s_lshl_b32 s30, s41, 15
	s_add_i32 s30, s30, 0
	ds_read_b64_tr_b16 v[80:81], v163 offset:0x200
	ds_read_b64_tr_b16 v[82:83], v163 offset:0xa00
	s_waitcnt lgkmcnt(7)
	v_mfma_f32_32x32x16_bf16 v[48:63], v[244:247], v[84:87], v[48:63]
	s_waitcnt vmcnt(4)
	ds_write_b128 v232, v[132:135]
	v_add_u32_e32 v232, s30, v196
	ds_read_b64_tr_b16 v[84:85], v163 offset:0x1200
	ds_read_b64_tr_b16 v[86:87], v163 offset:0x1a00
	s_waitcnt lgkmcnt(8)
	v_mfma_f32_32x32x16_bf16 v[48:63], v[248:251], v[88:91], v[48:63]
	v_add_u32_e32 v233, s30, v197
	s_waitcnt vmcnt(3)
	ds_write_b128 v232, v[136:139] offset:32768
	ds_read_b64_tr_b16 v[88:89], v163 offset:0x2200
	ds_read_b64_tr_b16 v[90:91], v163 offset:0x2a00
	ds_read_b64_tr_b16 v[228:229], v163 offset:0x3200
	ds_read_b64_tr_b16 v[230:231], v163 offset:0x3a00
	s_waitcnt lgkmcnt(11)
	v_mfma_f32_32x32x16_bf16 v[48:63], v[252:255], v[92:95], v[48:63]
	s_waitcnt vmcnt(1)
	ds_write_b128 v233, v[140:143] offset:32768
	s_waitcnt vmcnt(1)
	s_waitcnt lgkmcnt(9)
	v_mfma_f32_32x32x16_bf16 v[32:47], v[240:243], v[80:83], v[32:47]
	ds_write_b128 v232, v[144:147] offset:49152
	s_waitcnt vmcnt(0)
	ds_write_b128 v233, v[148:151] offset:49152
	ds_read_b64_tr_b16 v[80:81], v163 offset:0x400
	ds_read_b64_tr_b16 v[82:83], v163 offset:0xc00
	s_waitcnt lgkmcnt(10)
	v_mfma_f32_32x32x16_bf16 v[32:47], v[244:247], v[84:87], v[32:47]
	v_lshl_add_u64 v[232:233], v[188:189], 0, s[28:29]
	v_add_co_u32_e32 v234, vcc, 0xeb60000, v232
	s_nop 1
	ds_read_b64_tr_b16 v[84:85], v163 offset:0x1400
	ds_read_b64_tr_b16 v[86:87], v163 offset:0x1c00
	s_waitcnt lgkmcnt(9)
	v_mfma_f32_32x32x16_bf16 v[32:47], v[248:251], v[88:91], v[32:47]
	v_addc_co_u32_e32 v235, vcc, 0, v233, vcc
	v_add_co_u32_e32 v232, vcc, 0xeb70000, v232
	s_nop 1
	ds_read_b64_tr_b16 v[88:89], v163 offset:0x2400
	ds_read_b64_tr_b16 v[90:91], v163 offset:0x2c00
	ds_read_b64_tr_b16 v[92:93], v163 offset:0x3400
	ds_read_b64_tr_b16 v[94:95], v163 offset:0x3c00
	s_waitcnt lgkmcnt(11)
	v_mfma_f32_32x32x16_bf16 v[32:47], v[252:255], v[228:231], v[32:47]
	v_addc_co_u32_e32 v233, vcc, 0, v233, vcc
	global_load_dwordx4 v[128:131], v[234:235], off
	global_load_dwordx4 v[132:135], v[232:233], off
	s_waitcnt lgkmcnt(6)
	v_mfma_f32_32x32x16_bf16 v[16:31], v[240:243], v[80:83], v[16:31]
	v_lshl_add_u64 v[232:233], v[190:191], 0, s[28:29]
	v_add_co_u32_e32 v234, vcc, 0x10b60000, v232
	s_nop 1
	ds_read_b64_tr_b16 v[80:81], v163 offset:0x600
	ds_read_b64_tr_b16 v[82:83], v163 offset:0xe00
	s_waitcnt lgkmcnt(6)
	v_mfma_f32_32x32x16_bf16 v[16:31], v[244:247], v[84:87], v[16:31]
	v_addc_co_u32_e32 v235, vcc, 0, v233, vcc
	v_add_co_u32_e32 v232, vcc, 0x10b70000, v232
	s_nop 1
	ds_read_b64_tr_b16 v[84:85], v163 offset:0x1600
	ds_read_b64_tr_b16 v[86:87], v163 offset:0x1e00
	s_waitcnt lgkmcnt(6)
	v_mfma_f32_32x32x16_bf16 v[16:31], v[248:251], v[88:91], v[16:31]
	v_addc_co_u32_e32 v233, vcc, 0, v233, vcc
	global_load_dwordx4 v[136:139], v[234:235], off
	global_load_dwordx4 v[144:147], v[234:235], off offset:256
	ds_read_b64_tr_b16 v[88:89], v163 offset:0x2600
	ds_read_b64_tr_b16 v[90:91], v163 offset:0x2e00
	ds_read_b64_tr_b16 v[228:229], v163 offset:0x3600
	ds_read_b64_tr_b16 v[230:231], v163 offset:0x3e00
	s_waitcnt lgkmcnt(8)
	v_mfma_f32_32x32x16_bf16 v[16:31], v[252:255], v[92:95], v[16:31]
	global_load_dwordx4 v[140:143], v[232:233], off
	global_load_dwordx4 v[148:151], v[232:233], off offset:256
	s_waitcnt lgkmcnt(6)
	v_mfma_f32_32x32x16_bf16 v[0:15], v[240:243], v[80:83], v[0:15]
	s_waitcnt lgkmcnt(4)
	v_mfma_f32_32x32x16_bf16 v[0:15], v[244:247], v[84:87], v[0:15]
	s_waitcnt lgkmcnt(2)
	v_mfma_f32_32x32x16_bf16 v[0:15], v[248:251], v[88:91], v[0:15]
	s_waitcnt lgkmcnt(0)
	v_mfma_f32_32x32x16_bf16 v[0:15], v[252:255], v[228:231], v[0:15]
	s_branch .LBB0_380
